# v032: kind-5 (memory K/V tile) GEMM epilogue: the 8 row-group sum-of-squares loads issued together, one wait, no per-group vmcnt(0) store drains
# speedup vs baseline: 1.0063x; 1.0063x over previous
.LBB0_1088:
	s_and_b64 vcc, exec, s[50:51]
	s_cbranch_vccz .LBB0_1085
	s_waitcnt lgkmcnt(0)
	v_lshl_add_u64 v[128:129], v[144:145], 2, s[90:91]
	global_load_dword v130, v[128:129], off
	global_load_dword v176, v[128:129], off offset:64
	global_load_dword v177, v[128:129], off offset:128
	global_load_dword v178, v[128:129], off offset:192
	global_load_dword v179, v[128:129], off offset:512
	global_load_dword v180, v[128:129], off offset:576
	global_load_dword v181, v[128:129], off offset:640
	global_load_dword v182, v[128:129], off offset:704
	s_lshl_b32 s0, s66, 3
	v_add_u32_e32 v131, s4, v174
	s_add_i32 s16, s81, s0
	s_movk_i32 s0, 0x3ff
	v_cmp_lt_i32_e32 vcc, s0, v131
	s_movk_i32 s0, 0x400
	v_cmp_gt_i32_e64 s[0:1], s0, v131
	s_ashr_i32 s67, s66, 31
	v_mov_b32_e32 v129, v193
	v_cndmask_b32_e64 v128, v238, v239, s[0:1]
	s_lshl_b64 s[20:21], s[66:67], 23
	v_lshl_add_u64 v[128:129], s[86:87], 0, v[128:129]
	v_lshlrev_b64 v[146:147], 12, v[144:145]
	v_and_b32_e32 v132, 0x3ff, v131
	v_lshlrev_b32_e32 v131, 8, v131
	s_ashr_i32 s17, s16, 31
	v_lshl_add_u64 v[142:143], v[128:129], 0, s[20:21]
	v_mov_b32_e32 v139, v193
	v_lshlrev_b32_e32 v138, 2, v132
	v_and_b32_e32 v131, 0x30000, v131
	s_lshl_b64 s[30:31], s[16:17], 18
	v_lshl_add_u64 v[128:129], v[142:143], 0, v[146:147]
	v_or_b32_e32 v150, s30, v131
	v_mov_b32_e32 v151, s31
	v_lshl_add_u64 v[140:141], v[128:129], 0, v[138:139]
	v_ashrrev_i32_e32 v173, 31, v172
	v_lshlrev_b32_sdwa v136, v240, v174 dst_sel:DWORD dst_unused:UNUSED_PAD src0_sel:DWORD src1_sel:BYTE_0
	s_waitcnt vmcnt(0) lgkmcnt(0)
	v_fmamk_f32 v130, v130, 0x3a800000, v215
	v_rsq_f32_e32 v148, v130
	s_nop 0
	v_pk_mul_f32 v[134:135], v[126:127], v[148:149] op_sel_hi:[1,0]
	v_pk_mul_f32 v[132:133], v[124:125], v[148:149] op_sel_hi:[1,0]
	v_pk_mul_f32 v[130:131], v[122:123], v[148:149] op_sel_hi:[1,0]
	v_pk_mul_f32 v[128:129], v[120:121], v[148:149] op_sel_hi:[1,0]
	global_store_dwordx4 v[140:141], v[132:135], off
	global_store_dwordx4 v[140:141], v[128:131], off offset:16
	v_lshl_add_u64 v[140:141], v[150:151], 1, s[96:97]
	s_and_saveexec_b64 s[0:1], vcc
	s_xor_b64 s[0:1], exec, s[0:1]
	s_cbranch_execz .LBB0_1091
	v_mov_b32_e32 v137, v193
	v_lshl_add_u64 v[144:145], v[140:141], 0, v[136:137]
	v_lshl_add_u64 v[144:145], v[172:173], 1, v[144:145]
	v_cvt_pk_bf16_f32 v128, v128, s0
	global_store_short v[144:145], v128, off offset:2048
	v_cvt_pk_bf16_f32 v128, v133, s0
	global_store_short v[144:145], v128, off offset:512
	v_cvt_pk_bf16_f32 v128, v129, s0
	global_store_short v[144:145], v128, off offset:2560
	v_cvt_pk_bf16_f32 v128, v134, s0
	global_store_short v[144:145], v128, off offset:1024
	v_cvt_pk_bf16_f32 v128, v130, s0
	global_store_short v[144:145], v128, off offset:3072
	v_cvt_pk_bf16_f32 v128, v135, s0
	v_cvt_pk_bf16_f32 v132, v132, s0
	global_store_short v[144:145], v128, off offset:1536
	v_cvt_pk_bf16_f32 v128, v131, s0
	global_store_short v[144:145], v132, off
	global_store_short v[144:145], v128, off offset:3584

.LBB0_1097:
	s_or_b64 exec, exec, s[4:5]
	v_add_u32_e32 v164, 16, v172
	v_add_u32_e32 v128, s63, v164
	v_ashrrev_i32_e32 v129, 31, v128
	v_lshl_add_u64 v[130:131], v[128:129], 2, s[90:91]
	s_nop 0
	v_lshlrev_b64 v[160:161], 12, v[128:129]
	v_mov_b32_e32 v139, v193
	v_lshl_add_u64 v[128:129], v[142:143], 0, v[160:161]
	v_lshl_add_u64 v[166:167], v[128:129], 0, v[138:139]
	s_waitcnt lgkmcnt(0)
	v_fmamk_f32 v130, v176, 0x3a800000, v215
	v_rsq_f32_e32 v162, v130
	s_nop 0
	v_pk_mul_f32 v[134:135], v[118:119], v[162:163] op_sel_hi:[1,0]
	v_pk_mul_f32 v[132:133], v[116:117], v[162:163] op_sel_hi:[1,0]
	v_pk_mul_f32 v[130:131], v[114:115], v[162:163] op_sel_hi:[1,0]
	v_pk_mul_f32 v[128:129], v[112:113], v[162:163] op_sel_hi:[1,0]
	global_store_dwordx4 v[166:167], v[132:135], off
	global_store_dwordx4 v[166:167], v[128:131], off offset:16
	s_and_saveexec_b64 s[4:5], vcc
	s_xor_b64 s[4:5], exec, s[4:5]
	s_cbranch_execz .LBB0_1099
	v_mov_b32_e32 v137, v193
	v_lshl_add_u64 v[166:167], v[140:141], 0, v[136:137]
	v_lshl_add_u64 v[166:167], v[172:173], 1, v[166:167]
	v_cvt_pk_bf16_f32 v128, v128, s0
	global_store_short v[166:167], v128, off offset:2080
	v_cvt_pk_bf16_f32 v128, v133, s0
	global_store_short v[166:167], v128, off offset:544
	v_cvt_pk_bf16_f32 v128, v129, s0
	global_store_short v[166:167], v128, off offset:2592
	v_cvt_pk_bf16_f32 v128, v134, s0
	global_store_short v[166:167], v128, off offset:1056
	v_cvt_pk_bf16_f32 v128, v130, s0
	global_store_short v[166:167], v128, off offset:3104
	v_cvt_pk_bf16_f32 v128, v135, s0
	v_cvt_pk_bf16_f32 v132, v132, s0
	global_store_short v[166:167], v128, off offset:1568
	v_cvt_pk_bf16_f32 v128, v131, s0
	global_store_short v[166:167], v132, off offset:32
	global_store_short v[166:167], v128, off offset:3616

.LBB0_1105:
	s_or_b64 exec, exec, s[4:5]
	v_add_u32_e32 v164, 32, v172
	v_add_u32_e32 v128, s63, v164
	v_ashrrev_i32_e32 v129, 31, v128
	v_lshl_add_u64 v[130:131], v[128:129], 2, s[90:91]
	s_nop 0
	v_lshlrev_b64 v[160:161], 12, v[128:129]
	v_mov_b32_e32 v139, v193
	v_lshl_add_u64 v[128:129], v[142:143], 0, v[160:161]
	v_lshl_add_u64 v[166:167], v[128:129], 0, v[138:139]
	s_waitcnt lgkmcnt(0)
	v_fmamk_f32 v130, v177, 0x3a800000, v215
	v_rsq_f32_e32 v162, v130
	s_nop 0
	v_pk_mul_f32 v[134:135], v[110:111], v[162:163] op_sel_hi:[1,0]
	v_pk_mul_f32 v[132:133], v[108:109], v[162:163] op_sel_hi:[1,0]
	v_pk_mul_f32 v[130:131], v[106:107], v[162:163] op_sel_hi:[1,0]
	v_pk_mul_f32 v[128:129], v[104:105], v[162:163] op_sel_hi:[1,0]
	global_store_dwordx4 v[166:167], v[132:135], off
	global_store_dwordx4 v[166:167], v[128:131], off offset:16
	s_and_saveexec_b64 s[4:5], vcc
	s_xor_b64 s[4:5], exec, s[4:5]
	s_cbranch_execz .LBB0_1107
	v_mov_b32_e32 v137, v193
	v_lshl_add_u64 v[166:167], v[140:141], 0, v[136:137]
	v_lshl_add_u64 v[166:167], v[172:173], 1, v[166:167]
	v_cvt_pk_bf16_f32 v128, v128, s0
	global_store_short v[166:167], v128, off offset:2112
	v_cvt_pk_bf16_f32 v128, v133, s0
	global_store_short v[166:167], v128, off offset:576
	v_cvt_pk_bf16_f32 v128, v129, s0
	global_store_short v[166:167], v128, off offset:2624
	v_cvt_pk_bf16_f32 v128, v134, s0
	global_store_short v[166:167], v128, off offset:1088
	v_cvt_pk_bf16_f32 v128, v130, s0
	global_store_short v[166:167], v128, off offset:3136
	v_cvt_pk_bf16_f32 v128, v135, s0
	v_cvt_pk_bf16_f32 v132, v132, s0
	global_store_short v[166:167], v128, off offset:1600
	v_cvt_pk_bf16_f32 v128, v131, s0
	global_store_short v[166:167], v132, off offset:64
	global_store_short v[166:167], v128, off offset:3648

.LBB0_1113:
	s_or_b64 exec, exec, s[4:5]
	v_add_u32_e32 v164, 48, v172
	v_add_u32_e32 v128, s63, v164
	v_ashrrev_i32_e32 v129, 31, v128
	v_lshl_add_u64 v[130:131], v[128:129], 2, s[90:91]
	s_nop 0
	v_lshlrev_b64 v[160:161], 12, v[128:129]
	v_mov_b32_e32 v139, v193
	v_lshl_add_u64 v[128:129], v[142:143], 0, v[160:161]
	v_lshl_add_u64 v[166:167], v[128:129], 0, v[138:139]
	s_waitcnt lgkmcnt(0)
	v_fmamk_f32 v130, v178, 0x3a800000, v215
	v_rsq_f32_e32 v162, v130
	s_nop 0
	v_pk_mul_f32 v[134:135], v[102:103], v[162:163] op_sel_hi:[1,0]
	v_pk_mul_f32 v[132:133], v[100:101], v[162:163] op_sel_hi:[1,0]
	v_pk_mul_f32 v[130:131], v[98:99], v[162:163] op_sel_hi:[1,0]
	v_pk_mul_f32 v[128:129], v[96:97], v[162:163] op_sel_hi:[1,0]
	global_store_dwordx4 v[166:167], v[132:135], off
	global_store_dwordx4 v[166:167], v[128:131], off offset:16
	s_and_saveexec_b64 s[4:5], vcc
	s_xor_b64 s[4:5], exec, s[4:5]
	s_cbranch_execz .LBB0_1115
	v_mov_b32_e32 v137, v193
	v_lshl_add_u64 v[166:167], v[140:141], 0, v[136:137]
	v_lshl_add_u64 v[166:167], v[172:173], 1, v[166:167]
	v_cvt_pk_bf16_f32 v128, v128, s0
	global_store_short v[166:167], v128, off offset:2144
	v_cvt_pk_bf16_f32 v128, v133, s0
	global_store_short v[166:167], v128, off offset:608
	v_cvt_pk_bf16_f32 v128, v129, s0
	global_store_short v[166:167], v128, off offset:2656
	v_cvt_pk_bf16_f32 v128, v134, s0
	global_store_short v[166:167], v128, off offset:1120
	v_cvt_pk_bf16_f32 v128, v130, s0
	global_store_short v[166:167], v128, off offset:3168
	v_cvt_pk_bf16_f32 v128, v135, s0
	v_cvt_pk_bf16_f32 v132, v132, s0
	global_store_short v[166:167], v128, off offset:1632
	v_cvt_pk_bf16_f32 v128, v131, s0
	global_store_short v[166:167], v132, off offset:96
	global_store_short v[166:167], v128, off offset:3680

.LBB0_1121:
	s_or_b64 exec, exec, s[4:5]
	v_add_u32_e32 v164, 0x80, v172
	v_add_u32_e32 v128, s63, v164
	v_ashrrev_i32_e32 v129, 31, v128
	v_lshl_add_u64 v[130:131], v[128:129], 2, s[90:91]
	s_nop 0
	v_lshlrev_b64 v[160:161], 12, v[128:129]
	v_mov_b32_e32 v139, v193
	v_lshl_add_u64 v[128:129], v[142:143], 0, v[160:161]
	v_lshl_add_u64 v[166:167], v[128:129], 0, v[138:139]
	s_waitcnt lgkmcnt(0)
	v_fmamk_f32 v130, v179, 0x3a800000, v215
	v_rsq_f32_e32 v162, v130
	s_nop 0
	v_pk_mul_f32 v[134:135], v[62:63], v[162:163] op_sel_hi:[1,0]
	v_pk_mul_f32 v[132:133], v[60:61], v[162:163] op_sel_hi:[1,0]
	v_pk_mul_f32 v[130:131], v[58:59], v[162:163] op_sel_hi:[1,0]
	v_pk_mul_f32 v[128:129], v[56:57], v[162:163] op_sel_hi:[1,0]
	global_store_dwordx4 v[166:167], v[132:135], off
	global_store_dwordx4 v[166:167], v[128:131], off offset:16
	s_and_saveexec_b64 s[4:5], vcc
	s_xor_b64 s[4:5], exec, s[4:5]
	s_cbranch_execz .LBB0_1123
	v_mov_b32_e32 v137, v193
	v_lshl_add_u64 v[166:167], v[140:141], 0, v[136:137]
	v_lshl_add_u64 v[166:167], v[172:173], 1, v[166:167]
	v_cvt_pk_bf16_f32 v128, v128, s0
	global_store_short v[166:167], v128, off offset:2304
	v_cvt_pk_bf16_f32 v128, v133, s0
	global_store_short v[166:167], v128, off offset:768
	v_cvt_pk_bf16_f32 v128, v129, s0
	global_store_short v[166:167], v128, off offset:2816
	v_cvt_pk_bf16_f32 v128, v134, s0
	global_store_short v[166:167], v128, off offset:1280
	v_cvt_pk_bf16_f32 v128, v130, s0
	global_store_short v[166:167], v128, off offset:3328
	v_cvt_pk_bf16_f32 v128, v135, s0
	v_cvt_pk_bf16_f32 v132, v132, s0
	global_store_short v[166:167], v128, off offset:1792
	v_cvt_pk_bf16_f32 v128, v131, s0
	global_store_short v[166:167], v132, off offset:256
	global_store_short v[166:167], v128, off offset:3840

.LBB0_1129:
	s_or_b64 exec, exec, s[4:5]
	v_add_u32_e32 v164, 0x90, v172
	v_add_u32_e32 v128, s63, v164
	v_ashrrev_i32_e32 v129, 31, v128
	v_lshl_add_u64 v[130:131], v[128:129], 2, s[90:91]
	s_nop 0
	v_lshlrev_b64 v[160:161], 12, v[128:129]
	v_mov_b32_e32 v139, v193
	v_lshl_add_u64 v[128:129], v[142:143], 0, v[160:161]
	v_lshl_add_u64 v[166:167], v[128:129], 0, v[138:139]
	s_waitcnt lgkmcnt(0)
	v_fmamk_f32 v130, v180, 0x3a800000, v215
	v_rsq_f32_e32 v162, v130
	s_nop 0
	v_pk_mul_f32 v[134:135], v[54:55], v[162:163] op_sel_hi:[1,0]
	v_pk_mul_f32 v[132:133], v[52:53], v[162:163] op_sel_hi:[1,0]
	v_pk_mul_f32 v[130:131], v[50:51], v[162:163] op_sel_hi:[1,0]
	v_pk_mul_f32 v[128:129], v[48:49], v[162:163] op_sel_hi:[1,0]
	global_store_dwordx4 v[166:167], v[132:135], off
	global_store_dwordx4 v[166:167], v[128:131], off offset:16
	s_and_saveexec_b64 s[4:5], vcc
	s_xor_b64 s[4:5], exec, s[4:5]
	s_cbranch_execz .LBB0_1131
	v_mov_b32_e32 v137, v193
	v_lshl_add_u64 v[166:167], v[140:141], 0, v[136:137]
	v_lshl_add_u64 v[166:167], v[172:173], 1, v[166:167]
	v_cvt_pk_bf16_f32 v128, v128, s0
	global_store_short v[166:167], v128, off offset:2336
	v_cvt_pk_bf16_f32 v128, v133, s0
	global_store_short v[166:167], v128, off offset:800
	v_cvt_pk_bf16_f32 v128, v129, s0
	global_store_short v[166:167], v128, off offset:2848
	v_cvt_pk_bf16_f32 v128, v134, s0
	global_store_short v[166:167], v128, off offset:1312
	v_cvt_pk_bf16_f32 v128, v130, s0
	global_store_short v[166:167], v128, off offset:3360
	v_cvt_pk_bf16_f32 v128, v135, s0
	v_cvt_pk_bf16_f32 v132, v132, s0
	global_store_short v[166:167], v128, off offset:1824
	v_cvt_pk_bf16_f32 v128, v131, s0
	global_store_short v[166:167], v132, off offset:288
	global_store_short v[166:167], v128, off offset:3872

.LBB0_1137:
	s_or_b64 exec, exec, s[4:5]
	v_add_u32_e32 v164, 0xa0, v172
	v_add_u32_e32 v128, s63, v164
	v_ashrrev_i32_e32 v129, 31, v128
	v_lshl_add_u64 v[130:131], v[128:129], 2, s[90:91]
	s_nop 0
	v_lshlrev_b64 v[160:161], 12, v[128:129]
	v_mov_b32_e32 v139, v193
	v_lshl_add_u64 v[128:129], v[142:143], 0, v[160:161]
	v_lshl_add_u64 v[166:167], v[128:129], 0, v[138:139]
	s_waitcnt lgkmcnt(0)
	v_fmamk_f32 v130, v181, 0x3a800000, v215
	v_rsq_f32_e32 v162, v130
	s_nop 0
	v_pk_mul_f32 v[134:135], v[46:47], v[162:163] op_sel_hi:[1,0]
	v_pk_mul_f32 v[132:133], v[44:45], v[162:163] op_sel_hi:[1,0]
	v_pk_mul_f32 v[130:131], v[42:43], v[162:163] op_sel_hi:[1,0]
	v_pk_mul_f32 v[128:129], v[40:41], v[162:163] op_sel_hi:[1,0]
	global_store_dwordx4 v[166:167], v[132:135], off
	global_store_dwordx4 v[166:167], v[128:131], off offset:16
	s_and_saveexec_b64 s[4:5], vcc
	s_xor_b64 s[4:5], exec, s[4:5]
	s_cbranch_execz .LBB0_1139
	v_mov_b32_e32 v137, v193
	v_lshl_add_u64 v[166:167], v[140:141], 0, v[136:137]
	v_lshl_add_u64 v[166:167], v[172:173], 1, v[166:167]
	v_cvt_pk_bf16_f32 v128, v128, s0
	global_store_short v[166:167], v128, off offset:2368
	v_cvt_pk_bf16_f32 v128, v133, s0
	global_store_short v[166:167], v128, off offset:832
	v_cvt_pk_bf16_f32 v128, v129, s0
	global_store_short v[166:167], v128, off offset:2880
	v_cvt_pk_bf16_f32 v128, v134, s0
	global_store_short v[166:167], v128, off offset:1344
	v_cvt_pk_bf16_f32 v128, v130, s0
	global_store_short v[166:167], v128, off offset:3392
	v_cvt_pk_bf16_f32 v128, v135, s0
	v_cvt_pk_bf16_f32 v132, v132, s0
	global_store_short v[166:167], v128, off offset:1856
	v_cvt_pk_bf16_f32 v128, v131, s0
	global_store_short v[166:167], v132, off offset:320
	global_store_short v[166:167], v128, off offset:3904

.LBB0_1145:
	s_or_b64 exec, exec, s[4:5]
	v_add_u32_e32 v164, 0xb0, v172
	v_add_u32_e32 v128, s63, v164
	v_ashrrev_i32_e32 v129, 31, v128
	v_lshl_add_u64 v[130:131], v[128:129], 2, s[90:91]
	s_nop 0
	v_lshlrev_b64 v[160:161], 12, v[128:129]
	v_mov_b32_e32 v139, v193
	v_lshl_add_u64 v[128:129], v[142:143], 0, v[160:161]
	v_lshl_add_u64 v[138:139], v[128:129], 0, v[138:139]
	s_waitcnt lgkmcnt(0)
	v_fmamk_f32 v130, v182, 0x3a800000, v215
	v_rsq_f32_e32 v162, v130
	s_nop 0
	v_pk_mul_f32 v[134:135], v[38:39], v[162:163] op_sel_hi:[1,0]
	v_pk_mul_f32 v[132:133], v[36:37], v[162:163] op_sel_hi:[1,0]
	v_pk_mul_f32 v[130:131], v[34:35], v[162:163] op_sel_hi:[1,0]
	v_pk_mul_f32 v[128:129], v[32:33], v[162:163] op_sel_hi:[1,0]
	global_store_dwordx4 v[138:139], v[132:135], off
	global_store_dwordx4 v[138:139], v[128:131], off offset:16
	s_and_saveexec_b64 s[4:5], vcc
	s_xor_b64 s[4:5], exec, s[4:5]
	s_cbranch_execz .LBB0_1147
	v_mov_b32_e32 v137, v193
	v_lshl_add_u64 v[136:137], v[140:141], 0, v[136:137]
	v_lshl_add_u64 v[136:137], v[172:173], 1, v[136:137]
	v_cvt_pk_bf16_f32 v128, v128, s0
	global_store_short v[136:137], v128, off offset:2400
	v_cvt_pk_bf16_f32 v128, v133, s0
	global_store_short v[136:137], v128, off offset:864
	v_cvt_pk_bf16_f32 v128, v129, s0
	global_store_short v[136:137], v128, off offset:2912
	v_cvt_pk_bf16_f32 v128, v134, s0
	global_store_short v[136:137], v128, off offset:1376
	v_cvt_pk_bf16_f32 v128, v130, s0
	global_store_short v[136:137], v128, off offset:3424
	v_cvt_pk_bf16_f32 v128, v135, s0
	v_cvt_pk_bf16_f32 v132, v132, s0
	global_store_short v[136:137], v128, off offset:1888
	v_cvt_pk_bf16_f32 v128, v131, s0
	global_store_short v[136:137], v132, off offset:352
	global_store_short v[136:137], v128, off offset:3936
